# ssd dt prefetch early + attention ticket read via ds_read (no store drain)
# speedup vs baseline: 1.0043x; 1.0043x over previous
; __device__ __forceinline__ unsigned f2bf(float f) { return pk2(f, f) & 0xffffu; }
; #define BAR_LDS() asm volatile("s_waitcnt lgkmcnt(0)\n\ts_barrier" ::: "memory")
; template <bool DRY> __device__ __forceinline__ void ssd_unit(const Args& A, char* lds, int b, int h) {
;     ...
;         if (c + 1 < SEQL / 64) { const size_t o = (size_t)(c + 1) * 64 * 2048;
;             pre[0] = *(const bf16x8*)(pB + o); pre[1] = *(const bf16x8*)(pB + o + 32 * 2048); pre[2] = *(const bf16x8*)(pC + o); pre[3] = *(const bf16x8*)(pC + o + 32 * 2048); pre[4] = *(const bf16x8*)(pX + o); }
;         unsigned short zv[2][4];
; #pragma unroll
;         for (int pi = 0; pi < 2; ++pi)
; #pragma unroll
;             for (int r = 0; r < 4; ++r) zv[pi][r] = zn[pi][r];
;         if (c + 1 < SEQL / 64) {
; #pragma unroll
;             for (int pi = 0; pi < 2; ++pi)
; #pragma unroll
;                 for (int r = 0; r < 4; ++r) zn[pi][r] = pZ[((size_t)(c + 1) * 64 + r) * LD0 + 16 * pi]; }
;         BAR_LDS();
;         f32x4m cb[2], ya[2]; cb[0] = (f32x4m){0.f, 0.f, 0.f, 0.f}; cb[1] = cb[0]; ya[0] = cb[0]; ya[1] = cb[0];
; #pragma unroll
;         for (int ks = 0; ks < 4; ++ks) { const bf16x8 af = *(const bf16x8*)(CS + (lt * 16 + fr) * 136 + ks * 32 + 8 * fq);
; #pragma unroll
;             for (int si = 0; si < 2; ++si) { const bf16x8 bfv = *(const bf16x8*)(BS + ((st0 + si) * 16 + fr) * 136 + ks * 32 + 8 * fq); cb[si] = __builtin_amdgcn_mfma_f32_16x16x32_bf16(af, bfv, cb[si], 0, 0, 0); }
; #pragma unroll
;             for (int pi = 0; pi < 2; ++pi) { const bf16x8 sf = *(const bf16x8*)(SBF + ((pt0 + pi) * 16 + fr) * 136 + ks * 32 + 8 * fq); ya[pi] = __builtin_amdgcn_mfma_f32_16x16x32_bf16(af, sf, ya[pi], 0, 0, 0); } }
; #pragma unroll
;         for (int r = 0; r < 4; ++r) { const int l = lt * 16 + 4 * fq + r; const float al = DTA[64 + l];
; #pragma unroll
;             for (int si = 0; si < 2; ++si) { const int s = (st0 + si) * 16 + fr; const float v = (s <= l) ? cb[si][r] * __expf(al - DTA[64 + s]) : 0.f; GG[l * 72 + s] = (bf16)f2bf(v); }
;             const float ea = DTA[128 + l]; ya[0][r] *= ea; ya[1][r] *= ea; }
;         const float decay = __expf(DTA[64 + 63]);
;     ...
;             if (c + 2 < SEQL / 64) dtn = DT[(m0 + 128 + lane) * 16 + h]; }
.LBB0_821:
	s_or_b64 exec, exec, s[66:67]
	v_lshl_add_u64 v[16:17], v[76:77], 0, s[56:57]
	v_add_co_u32_e32 v18, vcc, 0x80000, v16
	v_add_u32_e32 v137, v68, v133
	s_nop 0
	v_addc_co_u32_e32 v19, vcc, 0, v17, vcc
	v_add_co_u32_e32 v16, vcc, 0xa0000, v16
	v_add_u32_e32 v138, v68, v134
	s_nop 0
	v_addc_co_u32_e32 v17, vcc, 0, v17, vcc
	v_add_co_u32_e32 v36, vcc, 0x1ca0000, v44
	flat_load_dwordx4 v[20:23], v[18:19] offset:2048
	flat_load_dwordx4 v[28:31], v[18:19] offset:2560
	flat_load_dwordx4 v[24:27], v[16:17] offset:2048
	flat_load_dwordx4 v[32:35], v[16:17] offset:2560
	v_addc_co_u32_e32 v37, vcc, 0, v45, vcc
	v_add_co_u32_e32 v38, vcc, 0x1ca3000, v44
	v_lshl_add_u64 v[16:17], v[80:81], 0, s[58:59]
	s_nop 0
	v_addc_co_u32_e32 v39, vcc, 0, v45, vcc
	v_add_co_u32_e32 v40, vcc, 0x1ca6000, v44
	flat_load_dwordx4 v[16:19], v[16:17]
	s_nop 0
	v_addc_co_u32_e32 v41, vcc, 0, v45, vcc
	v_add_co_u32_e32 v42, vcc, 0x1ca9000, v44
	v_lshl_add_u32 v85, v56, 2, s4
	s_nop 0
	v_addc_co_u32_e32 v43, vcc, 0, v45, vcc
	flat_load_ushort v131, v[36:37]
	flat_load_ushort v145, v[38:39] offset:1024
	flat_load_ushort v146, v[40:41] offset:2048
	flat_load_ushort v129, v[42:43] offset:3072
	flat_load_ushort v67, v[42:43] offset:3104
	flat_load_ushort v147, v[40:41] offset:2080
	flat_load_ushort v148, v[38:39] offset:1056
	flat_load_ushort v130, v[36:37] offset:32
	s_and_b64 s[98:99], exec, s[26:27]
	s_cbranch_scc1 .Lssd_dt_skip
	s_cmp_gt_u32 s1, 28
	s_cbranch_scc1 .Lssd_dt_skip
	flat_load_dword v255, v[74:75]
.Lssd_dt_skip:
	s_waitcnt lgkmcnt(0)
	s_barrier
	ds_read_b128 v[36:39], v64
	ds_read_b128 v[40:43], v137 offset:17408
	v_add_u32_e32 v142, v125, v133
	v_add_u32_e32 v139, v125, v134
	ds_read_b128 v[44:47], v138 offset:17408
	ds_read_b128 v[88:91], v64 offset:192
	ds_read_b32 v82, v85 offset:256
	ds_read_b128 v[48:51], v142
	ds_read_b128 v[150:153], v137 offset:17600
	ds_read_b128 v[154:157], v139
	ds_read_b128 v[158:161], v138 offset:17600
	s_waitcnt lgkmcnt(0)
	v_mfma_f32_16x16x32_bf16 v[40:43], v[36:39], v[40:43], 0
	ds_read_b128 v[162:165], v64 offset:64
	ds_read_b128 v[166:169], v142 offset:192
	v_lshl_add_u32 v87, v65, 2, s4
	v_mov_b32_e32 v83, 0
	v_mfma_f32_16x16x32_bf16 v[44:47], v[36:39], v[44:47], 0
	v_mfma_f32_16x16x32_bf16 v[48:51], v[36:39], v[48:51], 0
	v_mfma_f32_16x16x32_bf16 v[36:39], v[36:39], v[154:157], 0
	ds_read_b128 v[154:157], v137 offset:17472
	ds_read_b128 v[170:173], v64 offset:128
	ds_read_b128 v[174:177], v137 offset:17536
	s_waitcnt lgkmcnt(0)
	v_mfma_f32_16x16x32_bf16 v[40:43], v[162:165], v[154:157], v[40:43]
	ds_read_b128 v[154:157], v138 offset:17472
	ds_read_b128 v[178:181], v138 offset:17536
	s_waitcnt lgkmcnt(0)
	v_mfma_f32_16x16x32_bf16 v[44:47], v[162:165], v[154:157], v[44:47]
	ds_read_b128 v[154:157], v142 offset:64
	ds_read_b128 v[182:185], v142 offset:128
	s_waitcnt lgkmcnt(0)
	v_mfma_f32_16x16x32_bf16 v[48:51], v[162:165], v[154:157], v[48:51]
	ds_read_b128 v[154:157], v139 offset:64
	ds_read_b128 v[186:189], v139 offset:128
	v_mfma_f32_16x16x32_bf16 v[40:43], v[170:173], v[174:177], v[40:43]
	s_waitcnt lgkmcnt(0)
	v_mfma_f32_16x16x32_bf16 v[36:39], v[162:165], v[154:157], v[36:39]
	v_mfma_f32_16x16x32_bf16 v[154:157], v[170:173], v[182:185], v[48:51]
	v_mfma_f32_16x16x32_bf16 v[48:51], v[88:91], v[150:153], v[40:43]
	ds_read_b128 v[150:153], v139 offset:192
	v_mfma_f32_16x16x32_bf16 v[44:47], v[170:173], v[178:181], v[44:47]
	v_mfma_f32_16x16x32_bf16 v[36:39], v[170:173], v[186:189], v[36:39]
	v_mfma_f32_16x16x32_bf16 v[44:47], v[88:91], v[158:161], v[44:47]
	v_mfma_f32_16x16x32_bf16 v[40:43], v[88:91], v[166:169], v[154:157]
	s_waitcnt lgkmcnt(0)
	v_mfma_f32_16x16x32_bf16 v[36:39], v[88:91], v[150:153], v[36:39]
	v_mov_b32_e32 v89, 0
	s_and_saveexec_b64 s[66:67], s[6:7]
	s_cbranch_execz .LBB0_823
	ds_read_b32 v83, v87 offset:256
	s_waitcnt lgkmcnt(0)
	v_sub_f32_e32 v83, v82, v83
	v_mul_f32_e32 v83, 0x3fb8aa3b, v83
	v_exp_f32_e32 v83, v83
	s_nop 0
	v_mul_f32_e32 v48, v48, v83
	v_cvt_pk_bf16_f32 v83, v48, s0

; __device__ __forceinline__ unsigned f2bf(float f) { return pk2(f, f) & 0xffffu; }
; __device__ __forceinline__ float bf2f(unsigned short h) { return __uint_as_float(((unsigned)h) << 16); }
; __device__ __forceinline__ float row_sum16(float v) { v += dppf<0xB1>(v, v); v += dppf<0x4E>(v, v); v += dppf<0x141>(v, v); v += dppf<0x140>(v, v); return v; }
; __device__ __forceinline__ float rdlane(float v, int l) { return __builtin_bit_cast(float, __builtin_amdgcn_readlane(__builtin_bit_cast(int, v), l)); }
; __device__ __forceinline__ float silu_f(float x) { return x * __builtin_amdgcn_rcpf(1.f + __expf(-x)); }
; #define BAR_LDS() asm volatile("s_waitcnt lgkmcnt(0)\n\ts_barrier" ::: "memory")
; template <bool DRY> __device__ __forceinline__ void ssd_unit(const Args& A, char* lds, int b, int h) {
;     ...
;         unsigned short zv[2][4];
; #pragma unroll
;         for (int pi = 0; pi < 2; ++pi)
; #pragma unroll
;             for (int r = 0; r < 4; ++r) zv[pi][r] = zn[pi][r];
;     ...
;         for (int pi = 0; pi < 2; ++pi)
; #pragma unroll
;             for (int r = 0; r < 4; ++r) { const int l = lt * 16 + 4 * fq + r, p = (pt0 + pi) * 16 + fr;
;                 const float y = ya[pi][r] + Dh * bf2f(XS[l * 72 + p]);
;                 const float z = bf2f(zv[pi][r]); const float gt = y * silu_f(z);
;                 gts[pi][r] = (unsigned short)f2bf(gt); sqs[pi][r] = row_sum16(gt * gt); }
;         if (wave == 0 && c + 1 < SEQL / 64) { float* DN = DTA0 + ((c + 1) & 1) * 256; const float s = wave_scan(Ah * dtn, lane); const float tot = rdlane(s, 63);
;             DN[lane] = dtn; DN[64 + lane] = s; DN[128 + lane] = __expf(s); DN[192 + lane] = __expf(tot - s);
;             if (c + 2 < SEQL / 64) dtn = DT[(m0 + 128 + lane) * 16 + h]; }
;         BAR_LDS();
;     }
.LBB0_846:
	s_waitcnt lgkmcnt(0)
	s_barrier
	v_cvt_pk_bf16_f32 v151, v36, s0
	v_pk_add_f32 v[42:43], v[48:49], v[50:51]
	v_cvt_pk_bf16_f32 v149, v47, s0
	v_pk_add_f32 v[40:41], v[82:83], v[84:85]
	v_cvt_pk_bf16_f32 v82, v92, s0
	v_cvt_pk_bf16_f32 v50, v93, s0
	s_addk_i32 s0, 0x100
	v_cvt_pk_bf16_f32 v150, v44, v45
	v_cvt_pk_bf16_f32 v51, v86, v87
	v_pk_add_f32 v[38:39], v[88:89], v[90:91]
	v_pk_add_f32 v[36:37], v[94:95], v[96:97]
	s_waitcnt vmcnt(0)
	v_mov_b32_e32 v69, v255
	v_perm_b32 v86, v147, v148, s3
	v_perm_b32 v84, v146, v145, s3
	v_lshl_add_u64 v[72:73], v[72:73], 0, s[60:61]
	v_lshl_add_u64 v[74:75], v[74:75], 0, s[62:63]
	v_lshl_add_u64 v[76:77], v[76:77], 0, s[64:65]
	v_lshl_add_u64 v[78:79], v[78:79], 0, s[64:65]
	s_cmp_eq_u32 s1, 30
	v_lshl_add_u64 v[80:81], v[80:81], 0, s[64:65]
	s_cbranch_scc1 .LBB0_852
	v_mov_b32_e32 v94, v129
	v_mov_b32_e32 v97, v131
	v_mov_b32_e32 v96, v130
	v_mov_b32_e32 v95, v67
	s_branch .LBB0_811

; __device__ __forceinline__ int crow(int r,int hi){return (r&3)+8*(r>>2)+4*hi;}
; __device__ __forceinline__ unsigned cvtpk_s(float lo,float hi){f32x2_t v={lo,hi};bf16x2_t b=__builtin_convertvector(v,bf16x2_t);return __builtin_bit_cast(unsigned,b);}
; template<int THRL,int MODE,int DM,bool DRY=false> __device__ __forceinline__ void attn_unit(int b,int h,int qb,const bf16*Q,const bf16*__restrict__ K,const bf16*__restrict__ V,bf16*O,const bf16*__restrict__ Z,const float*__restrict__ XP,const int*__restrict__ TS,volatile unsigned*lw,unsigned nxt,cha ...
;     ...
;   float rli[16];
;   #pragma unroll
;   for(int r=0;r<16;++r)rli[r]=__builtin_amdgcn_rcpf(wsf[32+crow(r,hi)]);
;   bf16*Ow=O+(rowbase+q0+wid*QBLK)*DM+h*D;
;   { bf16*stg=(bf16*)(shm+LDS_OST)+wid*2048;
;     #pragma unroll
;     for(int r=0;r<16;++r){const int orow=crow(r,hi);
;       #pragma unroll
;       for(int d0=0;d0<2;++d0)stg[orow*64+d0*32+r32]=__float2bfloat16(o[d0][r]*rli[r]);}
;     asm volatile("s_waitcnt lgkmcnt(0)":::"memory");
;     #pragma unroll
;     for(int i=0;i<4;++i){const int row=i*8+(lane>>3),ch=lane&7; const u32x4 v=*(const u32x4*)(stg+row*64+ch*8); const u32x4 zv=zpre[i]; u32x4 ov;
;       #pragma unroll
;       for(int e=0;e<4;++e){ const float o0=__uint_as_float(v[e]<<16),o1=__uint_as_float(v[e]&0xffff0000u),z0=__uint_as_float(zv[e]<<16),z1=__uint_as_float(zv[e]&0xffff0000u);
;         ov[e]=cvtpk_s(o0*z0*__builtin_amdgcn_rcpf(1.f+__expf(-z0)),o1*z1*__builtin_amdgcn_rcpf(1.f+__expf(-z1))); }
;       if(!DRY||ov[0]==0x7fc12345u)ATTN_STORE16(Ow+(long)row*DM+ch*8,ov);} }
.LBB0_891:
	s_or_b64 exec, exec, s[8:9]
	s_waitcnt lgkmcnt(0)
	ds_read_b128 v[48:51], v98 offset:49280
	ds_read_b128 v[52:55], v98 offset:49312
	s_lshl_b32 s8, s65, 12
	s_add_i32 s8, s8, 0
	v_lshlrev_b32_e32 v64, 1, v237
	s_waitcnt lgkmcnt(0)
	v_rcp_f32_e32 v56, v48
	v_rcp_f32_e32 v57, v49
	v_lshlrev_b32_e32 v65, 9, v238
	v_add3_u32 v64, s8, v64, v65
	v_mul_f32_e32 v16, v16, v56
	v_cvt_pk_bf16_f32 v16, v16, s0
	v_rcp_f32_e32 v58, v50
	v_rcp_f32_e32 v59, v51
	v_rcp_f32_e32 v60, v52
	ds_read_b128 v[48:51], v98 offset:49344
	v_rcp_f32_e32 v61, v53
	v_rcp_f32_e32 v62, v54
	v_rcp_f32_e32 v63, v55
	ds_read_b128 v[52:55], v98 offset:49376
	ds_write_b16 v64, v16 offset:51200
	v_mul_f32_e32 v16, v32, v56
	v_cvt_pk_bf16_f32 v16, v16, s0
	ds_write_b16 v64, v16 offset:51264
	v_mul_f32_e32 v16, v17, v57
	v_cvt_pk_bf16_f32 v16, v16, s0
	ds_write_b16 v64, v16 offset:51328
	v_mul_f32_e32 v16, v33, v57
	v_cvt_pk_bf16_f32 v16, v16, s0
	ds_write_b16 v64, v16 offset:51392
	v_mul_f32_e32 v16, v18, v58
	v_cvt_pk_bf16_f32 v16, v16, s0
	ds_write_b16 v64, v16 offset:51456
	v_mul_f32_e32 v16, v34, v58
	v_cvt_pk_bf16_f32 v16, v16, s0
	ds_write_b16 v64, v16 offset:51520
	v_mul_f32_e32 v16, v19, v59
	v_cvt_pk_bf16_f32 v16, v16, s0
	ds_write_b16 v64, v16 offset:51584
	v_mul_f32_e32 v16, v35, v59
	v_cvt_pk_bf16_f32 v16, v16, s0
	ds_write_b16 v64, v16 offset:51648
	v_mul_f32_e32 v16, v20, v60
	v_cvt_pk_bf16_f32 v16, v16, s0
	ds_write_b16 v64, v16 offset:52224
	v_mul_f32_e32 v16, v36, v60
	v_cvt_pk_bf16_f32 v16, v16, s0
	ds_write_b16 v64, v16 offset:52288
	v_mul_f32_e32 v16, v21, v61
	v_cvt_pk_bf16_f32 v16, v16, s0
	ds_write_b16 v64, v16 offset:52352
	v_mul_f32_e32 v16, v37, v61
	v_cvt_pk_bf16_f32 v16, v16, s0
	ds_write_b16 v64, v16 offset:52416
	v_mul_f32_e32 v16, v22, v62
	v_cvt_pk_bf16_f32 v16, v16, s0
	ds_write_b16 v64, v16 offset:52480
	v_mul_f32_e32 v16, v38, v62
	v_cvt_pk_bf16_f32 v16, v16, s0
	s_waitcnt lgkmcnt(0)
	v_rcp_f32_e32 v48, v48
	ds_write_b16 v64, v16 offset:52544
	v_mul_f32_e32 v16, v23, v63
	v_cvt_pk_bf16_f32 v16, v16, s0
	ds_write_b16 v64, v16 offset:52608
	v_mul_f32_e32 v16, v39, v63
	v_cvt_pk_bf16_f32 v16, v16, s0
	v_rcp_f32_e32 v49, v49
	ds_write_b16 v64, v16 offset:52672
	v_mul_f32_e32 v16, v24, v48
	v_cvt_pk_bf16_f32 v16, v16, s0
	ds_write_b16 v64, v16 offset:53248
	v_mul_f32_e32 v16, v40, v48
	v_cvt_pk_bf16_f32 v16, v16, s0
	v_rcp_f32_e32 v50, v50
	ds_write_b16 v64, v16 offset:53312
	v_mul_f32_e32 v16, v25, v49
	v_cvt_pk_bf16_f32 v16, v16, s0
	ds_write_b16 v64, v16 offset:53376
	v_mul_f32_e32 v16, v41, v49
	v_cvt_pk_bf16_f32 v16, v16, s0
	v_rcp_f32_e32 v51, v51
	ds_write_b16 v64, v16 offset:53440
	v_mul_f32_e32 v16, v26, v50
	v_cvt_pk_bf16_f32 v16, v16, s0
	ds_write_b16 v64, v16 offset:53504
	v_mul_f32_e32 v16, v42, v50
	v_cvt_pk_bf16_f32 v16, v16, s0
	v_rcp_f32_e32 v52, v52
	ds_write_b16 v64, v16 offset:53568
	v_mul_f32_e32 v16, v27, v51
	v_cvt_pk_bf16_f32 v16, v16, s0
	ds_write_b16 v64, v16 offset:53632
	v_mul_f32_e32 v16, v43, v51
	v_cvt_pk_bf16_f32 v16, v16, s0
	v_rcp_f32_e32 v53, v53
	ds_write_b16 v64, v16 offset:53696
	v_mul_f32_e32 v16, v28, v52
	v_cvt_pk_bf16_f32 v16, v16, s0
	ds_write_b16 v64, v16 offset:54272
	v_mul_f32_e32 v16, v44, v52
	v_cvt_pk_bf16_f32 v16, v16, s0
	v_rcp_f32_e32 v54, v54
	ds_write_b16 v64, v16 offset:54336
	v_mul_f32_e32 v16, v29, v53
	v_cvt_pk_bf16_f32 v16, v16, s0
	ds_write_b16 v64, v16 offset:54400
	v_mul_f32_e32 v16, v45, v53
	v_cvt_pk_bf16_f32 v16, v16, s0
	v_rcp_f32_e32 v55, v55
	ds_write_b16 v64, v16 offset:54464
	v_mul_f32_e32 v16, v30, v54
	v_cvt_pk_bf16_f32 v16, v16, s0
	ds_write_b16 v64, v16 offset:54528
	v_mul_f32_e32 v16, v46, v54
	v_cvt_pk_bf16_f32 v16, v16, s0
	ds_write_b16 v64, v16 offset:54592
	v_mul_f32_e32 v16, v31, v55
	v_cvt_pk_bf16_f32 v16, v16, s0
	ds_write_b16 v64, v16 offset:54656
	v_mul_f32_e32 v16, v47, v55
	v_cvt_pk_bf16_f32 v16, v16, s0
	ds_write_b16 v64, v16 offset:54720
	v_lshlrev_b32_e32 v16, 7, v99
	s_waitcnt vmcnt(0)
	v_lshlrev_b32_e32 v20, 16, v92
	v_add3_u32 v30, s8, v222, v16
	v_and_b32_e32 v23, 0xffff0000, v92
	v_mul_f32_e32 v16, 0xbfb8aa3b, v20
	v_exp_f32_e32 v21, v16
	v_mul_f32_e32 v16, 0xbfb8aa3b, v23
	v_exp_f32_e32 v22, v16
	s_waitcnt lgkmcnt(0)
	ds_read_b128 v[16:19], v30 offset:51200
	v_add_f32_e32 v21, 1.0, v21
	v_rcp_f32_e32 v26, v21
	v_add_f32_e32 v21, 1.0, v22
	v_rcp_f32_e32 v27, v21
	s_waitcnt lgkmcnt(0)
	v_and_b32_e32 v21, 0xffff0000, v16
	v_lshlrev_b32_e32 v22, 16, v16
	v_pk_mul_f32 v[20:21], v[22:23], v[20:21]
	v_lshlrev_b32_e32 v22, 16, v93
	v_pk_mul_f32 v[20:21], v[26:27], v[20:21]
	v_and_b32_e32 v27, 0xffff0000, v93
	v_mul_f32_e32 v16, 0xbfb8aa3b, v22
	v_exp_f32_e32 v16, v16
	v_mul_f32_e32 v23, 0xbfb8aa3b, v27
	v_exp_f32_e32 v23, v23
	v_lshlrev_b32_e32 v26, 16, v17
	v_add_f32_e32 v16, 1.0, v16
	v_rcp_f32_e32 v28, v16
	v_add_f32_e32 v16, 1.0, v23
	v_and_b32_e32 v23, 0xffff0000, v17
	v_rcp_f32_e32 v29, v16
	v_pk_mul_f32 v[16:17], v[26:27], v[22:23]
	v_lshlrev_b32_e32 v22, 16, v94
	v_cvt_pk_bf16_f32 v20, v20, v21
	v_and_b32_e32 v27, 0xffff0000, v94
	v_mul_f32_e32 v21, 0xbfb8aa3b, v22
	v_exp_f32_e32 v23, v21
	v_mul_f32_e32 v21, 0xbfb8aa3b, v27
	v_exp_f32_e32 v26, v21
	v_pk_mul_f32 v[16:17], v[28:29], v[16:17]
	v_and_b32_e32 v29, 0xffff0000, v95
	v_cvt_pk_bf16_f32 v21, v16, v17
	v_add_f32_e32 v16, 1.0, v23
	v_add_f32_e32 v17, 1.0, v26
	v_rcp_f32_e32 v16, v16
	v_rcp_f32_e32 v17, v17
	v_and_b32_e32 v23, 0xffff0000, v18
	v_lshlrev_b32_e32 v26, 16, v18
	v_pk_mul_f32 v[22:23], v[26:27], v[22:23]
	v_lshlrev_b32_e32 v26, 16, v95
	v_pk_mul_f32 v[16:17], v[16:17], v[22:23]
	v_mul_f32_e32 v18, 0xbfb8aa3b, v26
	v_mul_f32_e32 v22, 0xbfb8aa3b, v29
	v_exp_f32_e32 v18, v18
	v_exp_f32_e32 v23, v22
	v_cvt_pk_bf16_f32 v22, v16, v17
	v_and_b32_e32 v27, 0xffff0000, v19
	v_add_f32_e32 v16, 1.0, v18
	v_add_f32_e32 v17, 1.0, v23
	v_rcp_f32_e32 v16, v16
	v_rcp_f32_e32 v17, v17
	v_lshlrev_b32_e32 v28, 16, v19
	v_pk_mul_f32 v[18:19], v[28:29], v[26:27]
	v_lshl_add_u64 v[24:25], s[58:59], 0, v[222:223]
	v_pk_mul_f32 v[16:17], v[16:17], v[18:19]
	v_mov_b32_e32 v97, v223
	v_cvt_pk_bf16_f32 v23, v16, v17
	v_lshl_add_u64 v[16:17], v[24:25], 0, v[96:97]
	flat_store_dwordx4 v[16:17], v[20:23]
	v_and_b32_e32 v25, 0xffff0000, v88
	s_cmp_lg_u32 s3, -1
	v_lshlrev_b32_e32 v22, 16, v88
	v_mul_f32_e32 v18, 0xbfb8aa3b, v22
	v_exp_f32_e32 v23, v18
	v_mul_f32_e32 v18, 0xbfb8aa3b, v25
	v_exp_f32_e32 v24, v18
	ds_read_b128 v[18:21], v30 offset:52224
	v_add_f32_e32 v23, 1.0, v23
	v_rcp_f32_e32 v26, v23
	v_add_f32_e32 v23, 1.0, v24
	v_rcp_f32_e32 v27, v23
	s_waitcnt lgkmcnt(0)
; __device__ __forceinline__ unsigned cvtpk_s(float lo,float hi){f32x2_t v={lo,hi};bf16x2_t b=__builtin_convertvector(v,bf16x2_t);return __builtin_bit_cast(unsigned,b);}
; #define BAR_LDS() asm volatile("s_waitcnt lgkmcnt(0)\n\ts_barrier" ::: "memory")
; template<int THRL,int MODE,int DM,bool DRY=false> __device__ __forceinline__ void attn_unit(int b,int h,int qb,const bf16*Q,const bf16*__restrict__ K,const bf16*__restrict__ V,bf16*O,const bf16*__restrict__ Z,const float*__restrict__ XP,const int*__restrict__ TS,volatile unsigned*lw,unsigned nxt,cha ...
;     ...
;     for(int i=0;i<4;++i){const int row=i*8+(lane>>3),ch=lane&7; const u32x4 v=*(const u32x4*)(stg+row*64+ch*8); const u32x4 zv=zpre[i]; u32x4 ov;
;       #pragma unroll
;       for(int e=0;e<4;++e){ const float o0=__uint_as_float(v[e]<<16),o1=__uint_as_float(v[e]&0xffff0000u),z0=__uint_as_float(zv[e]<<16),z1=__uint_as_float(zv[e]&0xffff0000u);
;         ov[e]=cvtpk_s(o0*z0*__builtin_amdgcn_rcpf(1.f+__expf(-z0)),o1*z1*__builtin_amdgcn_rcpf(1.f+__expf(-z1))); }
;       if(!DRY||ov[0]==0x7fc12345u)ATTN_STORE16(Ow+(long)row*DM+ch*8,ov);} }
;   asm volatile("s_waitcnt lgkmcnt(0)\n\ts_barrier":::"memory");
; template <bool DRY> __device__ __forceinline__ void moba_phase(const Args& A, char* lds, int vcu, int G) {
;     ...
;         BAR_LDS();
;         u = __builtin_amdgcn_readfirstlane((int)lw[0]);
	v_and_b32_e32 v23, 0xffff0000, v18
	v_lshlrev_b32_e32 v24, 16, v18
	v_pk_mul_f32 v[22:23], v[24:25], v[22:23]
	v_lshlrev_b32_e32 v24, 16, v89
	v_pk_mul_f32 v[22:23], v[26:27], v[22:23]
	v_and_b32_e32 v27, 0xffff0000, v89
	v_mul_f32_e32 v18, 0xbfb8aa3b, v24
	v_exp_f32_e32 v25, v18
	v_mul_f32_e32 v18, 0xbfb8aa3b, v27
	v_exp_f32_e32 v26, v18
	v_cvt_pk_bf16_f32 v18, v22, v23
	v_add_f32_e32 v22, 1.0, v25
	v_rcp_f32_e32 v22, v22
	v_add_f32_e32 v23, 1.0, v26
	v_rcp_f32_e32 v23, v23
	v_and_b32_e32 v25, 0xffff0000, v19
	v_lshlrev_b32_e32 v26, 16, v19
	v_pk_mul_f32 v[24:25], v[26:27], v[24:25]
	v_and_b32_e32 v27, 0xffff0000, v90
	v_pk_mul_f32 v[22:23], v[22:23], v[24:25]
	v_lshlrev_b32_e32 v24, 16, v90
	v_mul_f32_e32 v19, 0xbfb8aa3b, v24
	v_exp_f32_e32 v25, v19
	v_mul_f32_e32 v19, 0xbfb8aa3b, v27
	v_exp_f32_e32 v26, v19
	v_cvt_pk_bf16_f32 v19, v22, v23
	v_add_f32_e32 v22, 1.0, v25
	v_rcp_f32_e32 v22, v22
	v_add_f32_e32 v23, 1.0, v26
	v_rcp_f32_e32 v23, v23
	v_and_b32_e32 v25, 0xffff0000, v20
	v_lshlrev_b32_e32 v26, 16, v20
	v_pk_mul_f32 v[24:25], v[26:27], v[24:25]
	v_and_b32_e32 v27, 0xffff0000, v91
	v_pk_mul_f32 v[22:23], v[22:23], v[24:25]
	v_lshlrev_b32_e32 v24, 16, v91
	v_mul_f32_e32 v20, 0xbfb8aa3b, v24
	v_exp_f32_e32 v25, v20
	v_mul_f32_e32 v20, 0xbfb8aa3b, v27
	v_exp_f32_e32 v26, v20
	v_cvt_pk_bf16_f32 v20, v22, v23
	v_add_f32_e32 v22, 1.0, v25
	v_rcp_f32_e32 v22, v22
	v_add_f32_e32 v23, 1.0, v26
	v_rcp_f32_e32 v23, v23
	v_and_b32_e32 v25, 0xffff0000, v21
	v_lshlrev_b32_e32 v26, 16, v21
	v_pk_mul_f32 v[24:25], v[26:27], v[24:25]
	s_cselect_b32 s8, s3, 0
	v_pk_mul_f32 v[22:23], v[22:23], v[24:25]
	v_and_b32_e32 v25, 0xffff0000, v84
	v_cvt_pk_bf16_f32 v21, v22, v23
	v_add_co_u32_e32 v22, vcc, s1, v16
	s_cselect_b32 s9, s27, 0
	s_nop 0
	v_addc_co_u32_e32 v23, vcc, 0, v17, vcc
	flat_store_dwordx4 v[22:23], v[18:21]
	v_lshlrev_b32_e32 v22, 16, v84
	s_nop 0
	v_mul_f32_e32 v18, 0xbfb8aa3b, v22
	v_exp_f32_e32 v23, v18
	v_mul_f32_e32 v18, 0xbfb8aa3b, v25
	v_exp_f32_e32 v24, v18
	ds_read_b128 v[18:21], v30 offset:53248
	v_add_f32_e32 v23, 1.0, v23
	v_rcp_f32_e32 v26, v23
	v_add_f32_e32 v23, 1.0, v24
	v_rcp_f32_e32 v27, v23
	s_waitcnt lgkmcnt(0)
	v_and_b32_e32 v23, 0xffff0000, v18
	v_lshlrev_b32_e32 v24, 16, v18
	v_pk_mul_f32 v[22:23], v[24:25], v[22:23]
	v_lshlrev_b32_e32 v24, 16, v85
	v_pk_mul_f32 v[22:23], v[26:27], v[22:23]
	v_and_b32_e32 v27, 0xffff0000, v85
	v_mul_f32_e32 v18, 0xbfb8aa3b, v24
	v_exp_f32_e32 v25, v18
	v_mul_f32_e32 v18, 0xbfb8aa3b, v27
	v_exp_f32_e32 v26, v18
	v_cvt_pk_bf16_f32 v18, v22, v23
	v_add_f32_e32 v22, 1.0, v25
	v_rcp_f32_e32 v22, v22
	v_add_f32_e32 v23, 1.0, v26
	v_rcp_f32_e32 v23, v23
	v_and_b32_e32 v25, 0xffff0000, v19
	v_lshlrev_b32_e32 v26, 16, v19
	v_pk_mul_f32 v[24:25], v[26:27], v[24:25]
	v_and_b32_e32 v27, 0xffff0000, v86
	v_pk_mul_f32 v[22:23], v[22:23], v[24:25]
	v_lshlrev_b32_e32 v24, 16, v86
	v_mul_f32_e32 v19, 0xbfb8aa3b, v24
	v_exp_f32_e32 v25, v19
	v_mul_f32_e32 v19, 0xbfb8aa3b, v27
	v_exp_f32_e32 v26, v19
	v_cvt_pk_bf16_f32 v19, v22, v23
	v_add_f32_e32 v22, 1.0, v25
	v_rcp_f32_e32 v22, v22
	v_add_f32_e32 v23, 1.0, v26
	v_rcp_f32_e32 v23, v23
	v_and_b32_e32 v25, 0xffff0000, v20
	v_lshlrev_b32_e32 v26, 16, v20
	v_pk_mul_f32 v[24:25], v[26:27], v[24:25]
	v_and_b32_e32 v27, 0xffff0000, v87
	v_pk_mul_f32 v[22:23], v[22:23], v[24:25]
	v_lshlrev_b32_e32 v24, 16, v87
	v_mul_f32_e32 v20, 0xbfb8aa3b, v24
	v_exp_f32_e32 v25, v20
	v_mul_f32_e32 v20, 0xbfb8aa3b, v27
	v_exp_f32_e32 v26, v20
	v_cvt_pk_bf16_f32 v20, v22, v23
	v_add_f32_e32 v22, 1.0, v25
	v_rcp_f32_e32 v22, v22
	v_add_f32_e32 v23, 1.0, v26
	v_rcp_f32_e32 v23, v23
	v_and_b32_e32 v25, 0xffff0000, v21
	v_lshlrev_b32_e32 v26, 16, v21
	v_pk_mul_f32 v[24:25], v[26:27], v[24:25]
	s_nop 0
	v_pk_mul_f32 v[22:23], v[22:23], v[24:25]
	v_and_b32_e32 v25, 0xffff0000, v80
	v_cvt_pk_bf16_f32 v21, v22, v23
	v_add_co_u32_e32 v22, vcc, s89, v16
	s_nop 1
	v_addc_co_u32_e32 v23, vcc, 0, v17, vcc
	flat_store_dwordx4 v[22:23], v[18:21]
	v_lshlrev_b32_e32 v22, 16, v80
	v_add_co_u32_e32 v16, vcc, s90, v16
	v_mul_f32_e32 v18, 0xbfb8aa3b, v22
	v_exp_f32_e32 v23, v18
	v_mul_f32_e32 v18, 0xbfb8aa3b, v25
	v_exp_f32_e32 v24, v18
	ds_read_b128 v[18:21], v30 offset:54272
	v_add_f32_e32 v23, 1.0, v23
	v_rcp_f32_e32 v26, v23
	v_add_f32_e32 v23, 1.0, v24
	v_rcp_f32_e32 v27, v23
	s_waitcnt lgkmcnt(0)
	v_and_b32_e32 v23, 0xffff0000, v18
	v_lshlrev_b32_e32 v24, 16, v18
	v_pk_mul_f32 v[22:23], v[24:25], v[22:23]
	v_lshlrev_b32_e32 v24, 16, v81
	v_pk_mul_f32 v[22:23], v[26:27], v[22:23]
	v_and_b32_e32 v27, 0xffff0000, v81
	v_mul_f32_e32 v18, 0xbfb8aa3b, v24
	v_exp_f32_e32 v25, v18
	v_mul_f32_e32 v18, 0xbfb8aa3b, v27
	v_exp_f32_e32 v26, v18
	v_cvt_pk_bf16_f32 v18, v22, v23
	v_add_f32_e32 v22, 1.0, v25
	v_rcp_f32_e32 v22, v22
	v_add_f32_e32 v23, 1.0, v26
	v_rcp_f32_e32 v23, v23
	v_and_b32_e32 v25, 0xffff0000, v19
	v_lshlrev_b32_e32 v26, 16, v19
	v_pk_mul_f32 v[24:25], v[26:27], v[24:25]
	v_and_b32_e32 v27, 0xffff0000, v82
	v_pk_mul_f32 v[22:23], v[22:23], v[24:25]
	v_lshlrev_b32_e32 v24, 16, v82
	v_mul_f32_e32 v19, 0xbfb8aa3b, v24
	v_exp_f32_e32 v25, v19
	v_mul_f32_e32 v19, 0xbfb8aa3b, v27
	v_exp_f32_e32 v26, v19
	v_cvt_pk_bf16_f32 v19, v22, v23
	v_add_f32_e32 v22, 1.0, v25
	v_rcp_f32_e32 v22, v22
	v_add_f32_e32 v23, 1.0, v26
	v_rcp_f32_e32 v23, v23
	v_and_b32_e32 v25, 0xffff0000, v20
	v_lshlrev_b32_e32 v26, 16, v20
	v_pk_mul_f32 v[24:25], v[26:27], v[24:25]
	v_and_b32_e32 v27, 0xffff0000, v83
	v_pk_mul_f32 v[22:23], v[22:23], v[24:25]
	v_lshlrev_b32_e32 v24, 16, v83
	v_mul_f32_e32 v20, 0xbfb8aa3b, v24
	v_exp_f32_e32 v25, v20
	v_mul_f32_e32 v20, 0xbfb8aa3b, v27
	v_exp_f32_e32 v26, v20
	v_cvt_pk_bf16_f32 v20, v22, v23
	v_add_f32_e32 v22, 1.0, v25
	v_rcp_f32_e32 v22, v22
	v_add_f32_e32 v23, 1.0, v26
	v_rcp_f32_e32 v23, v23
	v_and_b32_e32 v25, 0xffff0000, v21
	v_lshlrev_b32_e32 v26, 16, v21
	v_pk_mul_f32 v[24:25], v[26:27], v[24:25]
	v_addc_co_u32_e32 v17, vcc, 0, v17, vcc
	v_pk_mul_f32 v[22:23], v[22:23], v[24:25]
	s_nop 0
	v_cvt_pk_bf16_f32 v21, v22, v23
	flat_store_dwordx4 v[16:17], v[18:21]
	s_waitcnt lgkmcnt(0)
	s_barrier
	s_waitcnt lgkmcnt(0)
	s_barrier
	v_mov_b32_e32 v16, s8
	v_mov_b32_e32 v17, s9
	ds_read_b32 v16, v16
	s_waitcnt lgkmcnt(0)
	v_readfirstlane_b32 s10, v16
	s_cmpk_lt_i32 s10, 0x400
	s_cbranch_scc0 .LBB0_984

; __device__ __forceinline__ int crow(int r,int hi){return (r&3)+8*(r>>2)+4*hi;}
; __device__ __forceinline__ unsigned cvtpk_s(float lo,float hi){f32x2_t v={lo,hi};bf16x2_t b=__builtin_convertvector(v,bf16x2_t);return __builtin_bit_cast(unsigned,b);}
; template<int THRL,int MODE,int DM,bool DRY=false> __device__ __forceinline__ void attn_unit(int b,int h,int qb,const bf16*Q,const bf16*__restrict__ K,const bf16*__restrict__ V,bf16*O,const bf16*__restrict__ Z,const float*__restrict__ XP,const int*__restrict__ TS,volatile unsigned*lw,unsigned nxt,cha ...
;     ...
;   float rli[16];
;   #pragma unroll
;   for(int r=0;r<16;++r)rli[r]=__builtin_amdgcn_rcpf(wsf[32+crow(r,hi)]);
;   bf16*Ow=O+(rowbase+q0+wid*QBLK)*DM+h*D;
;   { bf16*stg=(bf16*)(shm+LDS_OST)+wid*2048;
;     #pragma unroll
;     for(int r=0;r<16;++r){const int orow=crow(r,hi);
;       #pragma unroll
;       for(int d0=0;d0<2;++d0)stg[orow*64+d0*32+r32]=__float2bfloat16(o[d0][r]*rli[r]);}
;     asm volatile("s_waitcnt lgkmcnt(0)":::"memory");
;     #pragma unroll
;     for(int i=0;i<4;++i){const int row=i*8+(lane>>3),ch=lane&7; const u32x4 v=*(const u32x4*)(stg+row*64+ch*8); const u32x4 zv=zpre[i]; u32x4 ov;
;       #pragma unroll
;       for(int e=0;e<4;++e){ const float o0=__uint_as_float(v[e]<<16),o1=__uint_as_float(v[e]&0xffff0000u),z0=__uint_as_float(zv[e]<<16),z1=__uint_as_float(zv[e]&0xffff0000u);
;         ov[e]=cvtpk_s(o0*z0*__builtin_amdgcn_rcpf(1.f+__expf(-z0)),o1*z1*__builtin_amdgcn_rcpf(1.f+__expf(-z1))); }
;       if(!DRY||ov[0]==0x7fc12345u)ATTN_STORE16(Ow+(long)row*DM+ch*8,ov);} }
.LBB0_1435:
	s_or_b64 exec, exec, s[8:9]
	s_waitcnt lgkmcnt(0)
	ds_read_b128 v[32:35], v83 offset:49280
	ds_read_b128 v[36:39], v83 offset:49312
	s_lshl_b32 s8, s81, 12
	s_add_i32 s8, s8, 0
	v_lshlrev_b32_e32 v48, 1, v208
	s_waitcnt lgkmcnt(0)
	v_rcp_f32_e32 v40, v32
	v_rcp_f32_e32 v41, v33
	v_lshlrev_b32_e32 v49, 9, v209
	v_add3_u32 v48, s8, v48, v49
	v_mul_f32_e32 v0, v0, v40
	v_cvt_pk_bf16_f32 v0, v0, s0
	v_rcp_f32_e32 v42, v34
	v_rcp_f32_e32 v43, v35
	v_rcp_f32_e32 v44, v36
	ds_read_b128 v[32:35], v83 offset:49344
	v_rcp_f32_e32 v45, v37
	v_rcp_f32_e32 v46, v38
	v_rcp_f32_e32 v47, v39
	ds_read_b128 v[36:39], v83 offset:49376
	ds_write_b16 v48, v0 offset:51264
	v_mul_f32_e32 v0, v17, v41
	v_cvt_pk_bf16_f32 v0, v0, s0
	ds_write_b16 v48, v0 offset:51328
	v_mul_f32_e32 v0, v1, v41
	v_cvt_pk_bf16_f32 v0, v0, s0
	ds_write_b16 v48, v0 offset:51392
	v_mul_f32_e32 v0, v18, v42
	v_cvt_pk_bf16_f32 v0, v0, s0
	ds_write_b16 v48, v0 offset:51456
	v_mul_f32_e32 v0, v2, v42
	v_cvt_pk_bf16_f32 v0, v0, s0
	ds_write_b16 v48, v0 offset:51520
	v_mul_f32_e32 v0, v19, v43
	v_cvt_pk_bf16_f32 v0, v0, s0
	ds_write_b16 v48, v0 offset:51584
	v_mul_f32_e32 v0, v3, v43
	v_cvt_pk_bf16_f32 v0, v0, s0
	ds_write_b16 v48, v0 offset:51648
	v_mul_f32_e32 v0, v20, v44
	v_cvt_pk_bf16_f32 v0, v0, s0
	ds_write_b16 v48, v0 offset:52224
	v_mul_f32_e32 v0, v4, v44
	v_cvt_pk_bf16_f32 v0, v0, s0
	ds_write_b16 v48, v0 offset:52288
	v_mul_f32_e32 v0, v21, v45
	v_cvt_pk_bf16_f32 v0, v0, s0
	ds_write_b16 v48, v0 offset:52352
	v_mul_f32_e32 v0, v5, v45
	v_cvt_pk_bf16_f32 v0, v0, s0
	ds_write_b16 v48, v0 offset:52416
	v_mul_f32_e32 v0, v22, v46
	v_cvt_pk_bf16_f32 v0, v0, s0
	ds_write_b16 v48, v0 offset:52480
	v_mul_f32_e32 v0, v6, v46
	v_cvt_pk_bf16_f32 v0, v0, s0
	s_waitcnt lgkmcnt(0)
	v_rcp_f32_e32 v32, v32
	ds_write_b16 v48, v0 offset:52544
	v_mul_f32_e32 v0, v23, v47
	v_cvt_pk_bf16_f32 v0, v0, s0
	ds_write_b16 v48, v0 offset:52608
	v_mul_f32_e32 v0, v7, v47
	v_cvt_pk_bf16_f32 v0, v0, s0
	v_rcp_f32_e32 v33, v33
	ds_write_b16 v48, v0 offset:52672
	v_mul_f32_e32 v0, v24, v32
	v_cvt_pk_bf16_f32 v0, v0, s0
	ds_write_b16 v48, v0 offset:53248
	v_mul_f32_e32 v0, v8, v32
	v_cvt_pk_bf16_f32 v0, v0, s0
	v_rcp_f32_e32 v34, v34
	ds_write_b16 v48, v0 offset:53312
	v_mul_f32_e32 v0, v25, v33
	v_cvt_pk_bf16_f32 v0, v0, s0
	ds_write_b16 v48, v0 offset:53376
	v_mul_f32_e32 v0, v9, v33
	v_cvt_pk_bf16_f32 v0, v0, s0
	v_rcp_f32_e32 v35, v35
	ds_write_b16 v48, v0 offset:53440
	v_mul_f32_e32 v0, v26, v34
	v_cvt_pk_bf16_f32 v0, v0, s0
	ds_write_b16 v48, v0 offset:53504
	v_mul_f32_e32 v0, v10, v34
	v_cvt_pk_bf16_f32 v0, v0, s0
	v_rcp_f32_e32 v36, v36
	ds_write_b16 v48, v0 offset:53568
	v_mul_f32_e32 v0, v27, v35
	v_cvt_pk_bf16_f32 v0, v0, s0
	ds_write_b16 v48, v0 offset:53632
	v_mul_f32_e32 v0, v11, v35
	v_cvt_pk_bf16_f32 v0, v0, s0
	v_rcp_f32_e32 v37, v37
	ds_write_b16 v48, v0 offset:53696
	v_mul_f32_e32 v0, v28, v36
	v_cvt_pk_bf16_f32 v0, v0, s0
	ds_write_b16 v48, v0 offset:54272
	v_mul_f32_e32 v0, v12, v36
	v_cvt_pk_bf16_f32 v0, v0, s0
	v_rcp_f32_e32 v38, v38
	ds_write_b16 v48, v0 offset:54336
	v_mul_f32_e32 v0, v29, v37
	v_cvt_pk_bf16_f32 v0, v0, s0
	ds_write_b16 v48, v0 offset:54400
	v_mul_f32_e32 v0, v13, v37
	v_cvt_pk_bf16_f32 v0, v0, s0
	v_rcp_f32_e32 v39, v39
	ds_write_b16 v48, v0 offset:54464
	v_mul_f32_e32 v0, v30, v38
	v_cvt_pk_bf16_f32 v0, v0, s0
	ds_write_b16 v48, v0 offset:54528
	v_mul_f32_e32 v0, v14, v38
	v_cvt_pk_bf16_f32 v0, v0, s0
	ds_write_b16 v48, v0 offset:54592
	v_mul_f32_e32 v0, v31, v39
	v_cvt_pk_bf16_f32 v0, v0, s0
	ds_write_b16 v48, v0 offset:54656
	v_mul_f32_e32 v0, v15, v39
	v_cvt_pk_bf16_f32 v0, v0, s0
	ds_write_b16 v48, v0 offset:54720
	v_lshlrev_b32_e32 v0, 7, v84
	s_waitcnt vmcnt(0)
	v_lshlrev_b32_e32 v4, 16, v76
	v_mul_f32_e32 v16, v16, v40
	v_add3_u32 v14, s8, v192, v0
	v_and_b32_e32 v7, 0xffff0000, v76
	v_mul_f32_e32 v0, 0xbfb8aa3b, v4
	v_cvt_pk_bf16_f32 v16, v16, s0
	v_exp_f32_e32 v5, v0
	v_mul_f32_e32 v0, 0xbfb8aa3b, v7
	ds_write_b16 v48, v16 offset:51200
	v_exp_f32_e32 v6, v0
	s_waitcnt lgkmcnt(0)
	ds_read_b128 v[0:3], v14 offset:51200
	v_add_f32_e32 v5, 1.0, v5
	v_rcp_f32_e32 v10, v5
	v_add_f32_e32 v5, 1.0, v6
	v_rcp_f32_e32 v11, v5
	s_waitcnt lgkmcnt(0)
	v_and_b32_e32 v5, 0xffff0000, v0
	v_lshlrev_b32_e32 v6, 16, v0
	v_pk_mul_f32 v[4:5], v[6:7], v[4:5]
	v_lshlrev_b32_e32 v6, 16, v77
	v_pk_mul_f32 v[4:5], v[10:11], v[4:5]
	v_and_b32_e32 v11, 0xffff0000, v77
	v_mul_f32_e32 v0, 0xbfb8aa3b, v6
	v_exp_f32_e32 v0, v0
	v_mul_f32_e32 v7, 0xbfb8aa3b, v11
	v_exp_f32_e32 v7, v7
	v_lshlrev_b32_e32 v10, 16, v1
	v_add_f32_e32 v0, 1.0, v0
	v_rcp_f32_e32 v12, v0
	v_add_f32_e32 v0, 1.0, v7
	v_and_b32_e32 v7, 0xffff0000, v1
	v_rcp_f32_e32 v13, v0
	v_pk_mul_f32 v[0:1], v[10:11], v[6:7]
	v_lshlrev_b32_e32 v6, 16, v78
	v_cvt_pk_bf16_f32 v4, v4, v5
	v_and_b32_e32 v11, 0xffff0000, v78
	v_mul_f32_e32 v5, 0xbfb8aa3b, v6
	v_exp_f32_e32 v7, v5
	v_mul_f32_e32 v5, 0xbfb8aa3b, v11
	v_exp_f32_e32 v10, v5
	v_pk_mul_f32 v[0:1], v[12:13], v[0:1]
	v_and_b32_e32 v13, 0xffff0000, v79
	v_cvt_pk_bf16_f32 v5, v0, v1
	v_add_f32_e32 v0, 1.0, v7
	v_add_f32_e32 v1, 1.0, v10
	v_rcp_f32_e32 v0, v0
	v_rcp_f32_e32 v1, v1
	v_and_b32_e32 v7, 0xffff0000, v2
	v_lshlrev_b32_e32 v10, 16, v2
	v_pk_mul_f32 v[6:7], v[10:11], v[6:7]
	v_lshlrev_b32_e32 v10, 16, v79
	v_pk_mul_f32 v[0:1], v[0:1], v[6:7]
	v_mul_f32_e32 v2, 0xbfb8aa3b, v10
	v_mul_f32_e32 v6, 0xbfb8aa3b, v13
	v_exp_f32_e32 v2, v2
	v_exp_f32_e32 v7, v6
	v_cvt_pk_bf16_f32 v6, v0, v1
	v_and_b32_e32 v11, 0xffff0000, v3
	v_add_f32_e32 v0, 1.0, v2
	v_add_f32_e32 v1, 1.0, v7
	v_rcp_f32_e32 v0, v0
	v_rcp_f32_e32 v1, v1
	v_lshlrev_b32_e32 v12, 16, v3
	v_pk_mul_f32 v[2:3], v[12:13], v[10:11]
	v_lshl_add_u64 v[8:9], s[50:51], 0, v[192:193]
	v_pk_mul_f32 v[0:1], v[0:1], v[2:3]
	v_mov_b32_e32 v81, v193
	v_cvt_pk_bf16_f32 v7, v0, v1
	v_lshl_add_u64 v[0:1], v[8:9], 0, v[80:81]
	flat_store_dwordx4 v[0:1], v[4:7]
	v_and_b32_e32 v9, 0xffff0000, v72
	s_cmp_lg_u32 s3, -1
	v_lshlrev_b32_e32 v6, 16, v72
	v_mul_f32_e32 v2, 0xbfb8aa3b, v6
	v_exp_f32_e32 v7, v2
	v_mul_f32_e32 v2, 0xbfb8aa3b, v9
	v_exp_f32_e32 v8, v2
	ds_read_b128 v[2:5], v14 offset:52224
	v_add_f32_e32 v7, 1.0, v7
	v_rcp_f32_e32 v10, v7
	v_add_f32_e32 v7, 1.0, v8
	v_rcp_f32_e32 v11, v7
	s_waitcnt lgkmcnt(0)
; __device__ __forceinline__ unsigned cvtpk_s(float lo,float hi){f32x2_t v={lo,hi};bf16x2_t b=__builtin_convertvector(v,bf16x2_t);return __builtin_bit_cast(unsigned,b);}
; #define BAR_LDS() asm volatile("s_waitcnt lgkmcnt(0)\n\ts_barrier" ::: "memory")
; template<int THRL,int MODE,int DM,bool DRY=false> __device__ __forceinline__ void attn_unit(int b,int h,int qb,const bf16*Q,const bf16*__restrict__ K,const bf16*__restrict__ V,bf16*O,const bf16*__restrict__ Z,const float*__restrict__ XP,const int*__restrict__ TS,volatile unsigned*lw,unsigned nxt,cha ...
;     ...
;     for(int i=0;i<4;++i){const int row=i*8+(lane>>3),ch=lane&7; const u32x4 v=*(const u32x4*)(stg+row*64+ch*8); const u32x4 zv=zpre[i]; u32x4 ov;
;       #pragma unroll
;       for(int e=0;e<4;++e){ const float o0=__uint_as_float(v[e]<<16),o1=__uint_as_float(v[e]&0xffff0000u),z0=__uint_as_float(zv[e]<<16),z1=__uint_as_float(zv[e]&0xffff0000u);
;         ov[e]=cvtpk_s(o0*z0*__builtin_amdgcn_rcpf(1.f+__expf(-z0)),o1*z1*__builtin_amdgcn_rcpf(1.f+__expf(-z1))); }
;       if(!DRY||ov[0]==0x7fc12345u)ATTN_STORE16(Ow+(long)row*DM+ch*8,ov);} }
;   asm volatile("s_waitcnt lgkmcnt(0)\n\ts_barrier":::"memory");
; template <bool DRY> __device__ __forceinline__ void fox_phase(const Args& A, char* lds, int vcu, int G) {
;     ...
;         BAR_LDS();
;         u = __builtin_amdgcn_readfirstlane((int)lw[0]);
	v_and_b32_e32 v7, 0xffff0000, v2
	v_lshlrev_b32_e32 v8, 16, v2
	v_pk_mul_f32 v[6:7], v[8:9], v[6:7]
	v_lshlrev_b32_e32 v8, 16, v73
	v_pk_mul_f32 v[6:7], v[10:11], v[6:7]
	v_and_b32_e32 v11, 0xffff0000, v73
	v_mul_f32_e32 v2, 0xbfb8aa3b, v8
	v_exp_f32_e32 v9, v2
	v_mul_f32_e32 v2, 0xbfb8aa3b, v11
	v_exp_f32_e32 v10, v2
	v_cvt_pk_bf16_f32 v2, v6, v7
	v_add_f32_e32 v6, 1.0, v9
	v_rcp_f32_e32 v6, v6
	v_add_f32_e32 v7, 1.0, v10
	v_rcp_f32_e32 v7, v7
	v_and_b32_e32 v9, 0xffff0000, v3
	v_lshlrev_b32_e32 v10, 16, v3
	v_pk_mul_f32 v[8:9], v[10:11], v[8:9]
	v_and_b32_e32 v11, 0xffff0000, v74
	v_pk_mul_f32 v[6:7], v[6:7], v[8:9]
	v_lshlrev_b32_e32 v8, 16, v74
	v_mul_f32_e32 v3, 0xbfb8aa3b, v8
	v_exp_f32_e32 v9, v3
	v_mul_f32_e32 v3, 0xbfb8aa3b, v11
	v_exp_f32_e32 v10, v3
	v_cvt_pk_bf16_f32 v3, v6, v7
	v_add_f32_e32 v6, 1.0, v9
	v_rcp_f32_e32 v6, v6
	v_add_f32_e32 v7, 1.0, v10
	v_rcp_f32_e32 v7, v7
	v_and_b32_e32 v9, 0xffff0000, v4
	v_lshlrev_b32_e32 v10, 16, v4
	v_pk_mul_f32 v[8:9], v[10:11], v[8:9]
	v_and_b32_e32 v11, 0xffff0000, v75
	v_pk_mul_f32 v[6:7], v[6:7], v[8:9]
	v_lshlrev_b32_e32 v8, 16, v75
	v_mul_f32_e32 v4, 0xbfb8aa3b, v8
	v_exp_f32_e32 v9, v4
	v_mul_f32_e32 v4, 0xbfb8aa3b, v11
	v_exp_f32_e32 v10, v4
	v_cvt_pk_bf16_f32 v4, v6, v7
	v_add_f32_e32 v6, 1.0, v9
	v_rcp_f32_e32 v6, v6
	v_add_f32_e32 v7, 1.0, v10
	v_rcp_f32_e32 v7, v7
	v_and_b32_e32 v9, 0xffff0000, v5
	v_lshlrev_b32_e32 v10, 16, v5
	v_pk_mul_f32 v[8:9], v[10:11], v[8:9]
	s_cselect_b32 s8, s3, 0
	v_pk_mul_f32 v[6:7], v[6:7], v[8:9]
	v_and_b32_e32 v9, 0xffff0000, v68
	v_cvt_pk_bf16_f32 v5, v6, v7
	v_add_co_u32_e32 v6, vcc, s78, v0
	s_cselect_b32 s9, s19, 0
	s_nop 0
	v_addc_co_u32_e32 v7, vcc, 0, v1, vcc
	flat_store_dwordx4 v[6:7], v[2:5]
	v_lshlrev_b32_e32 v6, 16, v68
	s_nop 0
	v_mul_f32_e32 v2, 0xbfb8aa3b, v6
	v_exp_f32_e32 v7, v2
	v_mul_f32_e32 v2, 0xbfb8aa3b, v9
	v_exp_f32_e32 v8, v2
	ds_read_b128 v[2:5], v14 offset:53248
	v_add_f32_e32 v7, 1.0, v7
	v_rcp_f32_e32 v10, v7
	v_add_f32_e32 v7, 1.0, v8
	v_rcp_f32_e32 v11, v7
	s_waitcnt lgkmcnt(0)
	v_and_b32_e32 v7, 0xffff0000, v2
	v_lshlrev_b32_e32 v8, 16, v2
	v_pk_mul_f32 v[6:7], v[8:9], v[6:7]
	v_lshlrev_b32_e32 v8, 16, v69
	v_pk_mul_f32 v[6:7], v[10:11], v[6:7]
	v_and_b32_e32 v11, 0xffff0000, v69
	v_mul_f32_e32 v2, 0xbfb8aa3b, v8
	v_exp_f32_e32 v9, v2
	v_mul_f32_e32 v2, 0xbfb8aa3b, v11
	v_exp_f32_e32 v10, v2
	v_cvt_pk_bf16_f32 v2, v6, v7
	v_add_f32_e32 v6, 1.0, v9
	v_rcp_f32_e32 v6, v6
	v_add_f32_e32 v7, 1.0, v10
	v_rcp_f32_e32 v7, v7
	v_and_b32_e32 v9, 0xffff0000, v3
	v_lshlrev_b32_e32 v10, 16, v3
	v_pk_mul_f32 v[8:9], v[10:11], v[8:9]
	v_and_b32_e32 v11, 0xffff0000, v70
	v_pk_mul_f32 v[6:7], v[6:7], v[8:9]
	v_lshlrev_b32_e32 v8, 16, v70
	v_mul_f32_e32 v3, 0xbfb8aa3b, v8
	v_exp_f32_e32 v9, v3
	v_mul_f32_e32 v3, 0xbfb8aa3b, v11
	v_exp_f32_e32 v10, v3
	v_cvt_pk_bf16_f32 v3, v6, v7
	v_add_f32_e32 v6, 1.0, v9
	v_rcp_f32_e32 v6, v6
	v_add_f32_e32 v7, 1.0, v10
	v_rcp_f32_e32 v7, v7
	v_and_b32_e32 v9, 0xffff0000, v4
	v_lshlrev_b32_e32 v10, 16, v4
	v_pk_mul_f32 v[8:9], v[10:11], v[8:9]
	v_and_b32_e32 v11, 0xffff0000, v71
	v_pk_mul_f32 v[6:7], v[6:7], v[8:9]
	v_lshlrev_b32_e32 v8, 16, v71
	v_mul_f32_e32 v4, 0xbfb8aa3b, v8
	v_exp_f32_e32 v9, v4
	v_mul_f32_e32 v4, 0xbfb8aa3b, v11
	v_exp_f32_e32 v10, v4
	v_cvt_pk_bf16_f32 v4, v6, v7
	v_add_f32_e32 v6, 1.0, v9
	v_rcp_f32_e32 v6, v6
	v_add_f32_e32 v7, 1.0, v10
	v_rcp_f32_e32 v7, v7
	v_and_b32_e32 v9, 0xffff0000, v5
	v_lshlrev_b32_e32 v10, 16, v5
	v_pk_mul_f32 v[8:9], v[10:11], v[8:9]
	s_nop 0
	v_pk_mul_f32 v[6:7], v[6:7], v[8:9]
	v_and_b32_e32 v9, 0xffff0000, v64
	v_cvt_pk_bf16_f32 v5, v6, v7
	v_add_co_u32_e32 v6, vcc, s79, v0
	s_nop 1
	v_addc_co_u32_e32 v7, vcc, 0, v1, vcc
	flat_store_dwordx4 v[6:7], v[2:5]
	v_lshlrev_b32_e32 v6, 16, v64
	v_add_co_u32_e32 v0, vcc, s80, v0
	v_mul_f32_e32 v2, 0xbfb8aa3b, v6
	v_exp_f32_e32 v7, v2
	v_mul_f32_e32 v2, 0xbfb8aa3b, v9
	v_exp_f32_e32 v8, v2
	ds_read_b128 v[2:5], v14 offset:54272
	v_add_f32_e32 v7, 1.0, v7
	v_rcp_f32_e32 v10, v7
	v_add_f32_e32 v7, 1.0, v8
	v_rcp_f32_e32 v11, v7
	s_waitcnt lgkmcnt(0)
	v_and_b32_e32 v7, 0xffff0000, v2
	v_lshlrev_b32_e32 v8, 16, v2
	v_pk_mul_f32 v[6:7], v[8:9], v[6:7]
	v_lshlrev_b32_e32 v8, 16, v65
	v_pk_mul_f32 v[6:7], v[10:11], v[6:7]
	v_and_b32_e32 v11, 0xffff0000, v65
	v_mul_f32_e32 v2, 0xbfb8aa3b, v8
	v_exp_f32_e32 v9, v2
	v_mul_f32_e32 v2, 0xbfb8aa3b, v11
	v_exp_f32_e32 v10, v2
	v_cvt_pk_bf16_f32 v2, v6, v7
	v_add_f32_e32 v6, 1.0, v9
	v_rcp_f32_e32 v6, v6
	v_add_f32_e32 v7, 1.0, v10
	v_rcp_f32_e32 v7, v7
	v_and_b32_e32 v9, 0xffff0000, v3
	v_lshlrev_b32_e32 v10, 16, v3
	v_pk_mul_f32 v[8:9], v[10:11], v[8:9]
	v_and_b32_e32 v11, 0xffff0000, v66
	v_pk_mul_f32 v[6:7], v[6:7], v[8:9]
	v_lshlrev_b32_e32 v8, 16, v66
	v_mul_f32_e32 v3, 0xbfb8aa3b, v8
	v_exp_f32_e32 v9, v3
	v_mul_f32_e32 v3, 0xbfb8aa3b, v11
	v_exp_f32_e32 v10, v3
	v_cvt_pk_bf16_f32 v3, v6, v7
	v_add_f32_e32 v6, 1.0, v9
	v_rcp_f32_e32 v6, v6
	v_add_f32_e32 v7, 1.0, v10
	v_rcp_f32_e32 v7, v7
	v_and_b32_e32 v9, 0xffff0000, v4
	v_lshlrev_b32_e32 v10, 16, v4
	v_pk_mul_f32 v[8:9], v[10:11], v[8:9]
	v_and_b32_e32 v11, 0xffff0000, v67
	v_pk_mul_f32 v[6:7], v[6:7], v[8:9]
	v_lshlrev_b32_e32 v8, 16, v67
	v_mul_f32_e32 v4, 0xbfb8aa3b, v8
	v_exp_f32_e32 v9, v4
	v_mul_f32_e32 v4, 0xbfb8aa3b, v11
	v_exp_f32_e32 v10, v4
	v_cvt_pk_bf16_f32 v4, v6, v7
	v_add_f32_e32 v6, 1.0, v9
	v_rcp_f32_e32 v6, v6
	v_add_f32_e32 v7, 1.0, v10
	v_rcp_f32_e32 v7, v7
	v_and_b32_e32 v9, 0xffff0000, v5
	v_lshlrev_b32_e32 v10, 16, v5
	v_pk_mul_f32 v[8:9], v[10:11], v[8:9]
	v_addc_co_u32_e32 v1, vcc, 0, v1, vcc
	v_pk_mul_f32 v[6:7], v[6:7], v[8:9]
	s_nop 0
	v_cvt_pk_bf16_f32 v5, v6, v7
	flat_store_dwordx4 v[0:1], v[2:5]
	s_waitcnt lgkmcnt(0)
	s_barrier
	s_waitcnt lgkmcnt(0)
	s_barrier
	v_mov_b32_e32 v0, s8
	v_mov_b32_e32 v1, s9
	ds_read_b32 v0, v0
	s_waitcnt lgkmcnt(0)
	v_readfirstlane_b32 s10, v0
	s_cmpk_lt_i32 s10, 0x600
	s_cbranch_scc0 .LBB0_1531

; __global__ void __launch_bounds__(NTHR, 2) trunk_fwd(Args kargs_unused) {
	.amdhsa_kernel _Z9trunk_fwd4Args
		.amdhsa_group_segment_fixed_size 0
		.amdhsa_private_segment_fixed_size 0
		.amdhsa_kernarg_size 488
		.amdhsa_user_sgpr_count 2
		.amdhsa_user_sgpr_dispatch_ptr 0
		.amdhsa_user_sgpr_queue_ptr 0
		.amdhsa_user_sgpr_kernarg_segment_ptr 1
		.amdhsa_user_sgpr_dispatch_id 0
		.amdhsa_user_sgpr_kernarg_preload_length 0
		.amdhsa_user_sgpr_kernarg_preload_offset 0
		.amdhsa_user_sgpr_private_segment_size 0
		.amdhsa_uses_dynamic_stack 0
		.amdhsa_enable_private_segment 0
		.amdhsa_system_sgpr_workgroup_id_x 1
		.amdhsa_system_sgpr_workgroup_id_y 0
		.amdhsa_system_sgpr_workgroup_id_z 0
		.amdhsa_system_sgpr_workgroup_info 0
		.amdhsa_system_vgpr_workitem_id 2
		.amdhsa_next_free_vgpr 256
		.amdhsa_next_free_sgpr 102
		.amdhsa_accum_offset 256
		.amdhsa_reserve_vcc 1
		.amdhsa_float_round_mode_32 0
		.amdhsa_float_round_mode_16_64 0
		.amdhsa_float_denorm_mode_32 3
		.amdhsa_float_denorm_mode_16_64 3
		.amdhsa_dx10_clamp 1
		.amdhsa_ieee_mode 1
		.amdhsa_fp16_overflow 0
		.amdhsa_tg_split 0
		.amdhsa_exception_fp_ieee_invalid_op 0
		.amdhsa_exception_fp_denorm_src 0
		.amdhsa_exception_fp_ieee_div_zero 0
		.amdhsa_exception_fp_ieee_overflow 0
		.amdhsa_exception_fp_ieee_underflow 0
		.amdhsa_exception_fp_ieee_inexact 0
		.amdhsa_exception_int_div_zero 0
	.end_amdhsa_kernel

; __global__ void __launch_bounds__(NTHR, 2) trunk_fwd(Args kargs_unused) {
.Lfunc_end0:
	.size	_Z9trunk_fwd4Args, .Lfunc_end0-_Z9trunk_fwd4Args
	.set _Z9trunk_fwd4Args.num_vgpr, 256
	.set _Z9trunk_fwd4Args.num_agpr, 0
	.set _Z9trunk_fwd4Args.numbered_sgpr, 102
	.set _Z9trunk_fwd4Args.num_named_barrier, 0
	.set _Z9trunk_fwd4Args.private_seg_size, 0
	.set _Z9trunk_fwd4Args.uses_vcc, 1
	.set _Z9trunk_fwd4Args.uses_flat_scratch, 0
	.set _Z9trunk_fwd4Args.has_dyn_sized_stack, 0
	.set _Z9trunk_fwd4Args.has_recursion, 0
	.set _Z9trunk_fwd4Args.has_indirect_call, 0

; __global__ void __launch_bounds__(NTHR, 2) trunk_fwd(Args kargs_unused) {
amdhsa.kernels:
  - .agpr_count:     0
    .args:
      - .offset:         0
        .size:           232
        .value_kind:     by_value
      - .offset:         232
        .size:           4
        .value_kind:     hidden_block_count_x
      - .offset:         236
        .size:           4
        .value_kind:     hidden_block_count_y
      - .offset:         240
        .size:           4
        .value_kind:     hidden_block_count_z
      - .offset:         244
        .size:           2
        .value_kind:     hidden_group_size_x
      - .offset:         246
        .size:           2
        .value_kind:     hidden_group_size_y
      - .offset:         248
        .size:           2
        .value_kind:     hidden_group_size_z
      - .offset:         250
        .size:           2
        .value_kind:     hidden_remainder_x
      - .offset:         252
        .size:           2
        .value_kind:     hidden_remainder_y
      - .offset:         254
        .size:           2
        .value_kind:     hidden_remainder_z
      - .offset:         272
        .size:           8
        .value_kind:     hidden_global_offset_x
      - .offset:         280
        .size:           8
        .value_kind:     hidden_global_offset_y
      - .offset:         288
        .size:           8
        .value_kind:     hidden_global_offset_z
      - .offset:         296
        .size:           2
        .value_kind:     hidden_grid_dims
      - .offset:         320
        .size:           8
        .value_kind:     hidden_multigrid_sync_arg
      - .offset:         352
        .size:           4
        .value_kind:     hidden_dynamic_lds_size
    .group_segment_fixed_size: 0
    .kernarg_segment_align: 8
    .kernarg_segment_size: 488
    .language:       OpenCL C
    .language_version:
      - 2
      - 0
    .max_flat_workgroup_size: 512
    .name:           _Z9trunk_fwd4Args
    .private_segment_fixed_size: 0
    .sgpr_count:     108
    .sgpr_spill_count: 131
    .symbol:         _Z9trunk_fwd4Args.kd
    .uniform_work_group_size: 1
    .uses_dynamic_stack: false
    .vgpr_count:     256
    .vgpr_spill_count: 0
    .wavefront_size: 64
